# skip grid barrier between DFT GEMM phase and first scan phase (no dependency) + static prep assignment + wave0 latency fix
# speedup vs baseline: 1.0140x; 1.0131x over previous
.LBB0_334:
	s_or_b64 exec, exec, s[0:1]
	v_lshlrev_b32_e32 v3, 5, v52
	v_or_b32_e32 v4, v3, v53
	s_movk_i32 s0, 0x48
	v_mul_lo_u32 v18, v4, s0
	v_bitop3_b32 v19, v3, 56, v53 bitop3:0xc8
	v_or_b32_e32 v20, 32, v30
	v_mul_u32_u24_e32 v3, 0x48, v53
	v_xad_u32 v20, v20, v19, v18
	v_lshlrev_b32_e32 v2, 1, v30
	v_lshlrev_b32_e32 v3, 1, v3
	v_or_b32_e32 v14, 16, v30
	v_lshl_add_u32 v91, v20, 1, v146
	v_or_b32_e32 v20, 48, v30
	v_add3_u32 v90, v146, v2, v3
	v_xad_u32 v2, v30, v19, v18
	v_xad_u32 v14, v14, v19, v18
	v_xad_u32 v18, v20, v19, v18
	s_waitcnt lgkmcnt(0)
	s_barrier
	v_lshl_add_u32 v50, v2, 1, v146
	v_lshl_add_u32 v51, v14, 1, v146
	v_lshl_add_u32 v92, v18, 1, v146
	ds_read_b128 v[2:5], v50 offset:53248
	ds_read_b128 v[6:9], v50 offset:34816
	ds_read_b128 v[10:13], v90 offset:16384
	ds_read_b128 v[34:37], v90 offset:16416
	ds_read_b128 v[38:41], v51 offset:53248
	ds_read_b128 v[42:45], v51 offset:34816
	ds_read_b128 v[14:17], v90 offset:25600
	ds_read_b128 v[54:57], v90 offset:25632
	ds_read_b128 v[58:61], v91 offset:53248
	ds_read_b128 v[62:65], v91 offset:34816
	ds_read_b128 v[66:69], v90 offset:16448
	ds_read_b128 v[70:73], v90 offset:16480
	ds_read_b128 v[74:77], v92 offset:53248
	ds_read_b128 v[78:81], v92 offset:34816
	ds_read_b128 v[82:85], v90 offset:25664
	ds_read_b128 v[86:89], v90 offset:25696
	s_mov_b64 s[0:1], 0xe000
	v_lshl_add_u64 v[94:95], v[48:49], 0, s[0:1]
	v_lshlrev_b32_e32 v96, 5, v160
	s_waitcnt lgkmcnt(13)
	v_mfma_f32_32x32x16_bf16 v[18:33], v[10:13], v[2:5], 0
	v_lshlrev_b32_e32 v97, 11, v52
	v_lshlrev_b32_e32 v98, 4, v160
	s_waitcnt lgkmcnt(9)
	v_mfma_f32_32x32x16_bf16 v[2:17], v[6:9], v[14:17], 0
	v_mfma_f32_32x32x16_bf16 v[18:33], v[34:37], v[38:41], v[18:33]
	s_waitcnt lgkmcnt(8)
	v_mfma_f32_32x32x16_bf16 v[2:17], v[42:45], v[54:57], v[2:17]
	s_waitcnt lgkmcnt(5)
	v_mfma_f32_32x32x16_bf16 v[18:33], v[66:69], v[58:61], v[18:33]
	s_waitcnt lgkmcnt(1)
	v_mfma_f32_32x32x16_bf16 v[2:17], v[62:65], v[82:85], v[2:17]
	v_mfma_f32_32x32x16_bf16 v[18:33], v[70:73], v[74:77], v[18:33]
	s_waitcnt lgkmcnt(0)
	v_mfma_f32_32x32x16_bf16 v[2:17], v[78:81], v[86:89], v[2:17]
	s_nop 9
	v_cvt_pk_bf16_f32 v18, v18, v19
	v_cvt_pk_bf16_f32 v19, v20, v21
	v_cvt_pk_bf16_f32 v20, v22, v23
	v_cvt_pk_bf16_f32 v22, v26, v27
	v_or_b32_e32 v26, v97, v96
	v_ashrrev_i32_e32 v27, 31, v26
	v_cvt_pk_bf16_f32 v21, v24, v25
	v_cvt_pk_bf16_f32 v2, v2, v3
	v_cvt_pk_bf16_f32 v3, v4, v5
	v_cvt_pk_bf16_f32 v4, v6, v7
	v_or_b32_e32 v6, v97, v98
	v_cvt_pk_bf16_f32 v23, v28, v29
	v_lshl_add_u64 v[26:27], v[94:95], 0, v[26:27]
	v_ashrrev_i32_e32 v7, 31, v6
	v_cvt_pk_bf16_f32 v24, v30, v31
	v_cvt_pk_bf16_f32 v25, v32, v33
	global_store_dwordx4 v[26:27], v[18:21], off nt
	global_store_dwordx4 v[26:27], v[22:25], off offset:16 nt
	v_cvt_pk_bf16_f32 v5, v8, v9
	s_nop 0
	v_lshl_add_u64 v[22:23], v[48:49], 0, v[6:7]
	global_store_dwordx4 v[22:23], v[2:5], off nt
	ds_read_b128 v[6:9], v50 offset:53248
	ds_read_b128 v[34:37], v50 offset:34816
	ds_read_b128 v[18:21], v90 offset:20992
	ds_read_b128 v[38:41], v90 offset:21024
	ds_read_b128 v[42:45], v51 offset:53248
	ds_read_b128 v[50:53], v51 offset:34816
	ds_read_b128 v[54:57], v90 offset:30208
	ds_read_b128 v[58:61], v90 offset:30240
	ds_read_b128 v[62:65], v91 offset:53248
	ds_read_b128 v[66:69], v91 offset:34816
	ds_read_b128 v[70:73], v90 offset:21056
	ds_read_b128 v[74:77], v90 offset:21088
	ds_read_b128 v[78:81], v92 offset:53248
	ds_read_b128 v[82:85], v92 offset:34816
	ds_read_b128 v[86:89], v90 offset:30272
	ds_read_b128 v[90:93], v90 offset:30304
	v_cvt_pk_bf16_f32 v2, v10, v11
	v_cvt_pk_bf16_f32 v3, v12, v13
	v_cvt_pk_bf16_f32 v4, v14, v15
	v_cvt_pk_bf16_f32 v5, v16, v17
	global_store_dwordx4 v[22:23], v[2:5], off offset:1024 nt
	s_waitcnt lgkmcnt(13)
	v_mfma_f32_32x32x16_bf16 v[18:33], v[18:21], v[6:9], 0
	v_cmp_eq_u32_e32 vcc, 0, v148
	s_waitcnt lgkmcnt(9)
	v_mfma_f32_32x32x16_bf16 v[2:17], v[34:37], v[54:57], 0
	v_mfma_f32_32x32x16_bf16 v[18:33], v[38:41], v[42:45], v[18:33]
	s_waitcnt lgkmcnt(8)
	v_mfma_f32_32x32x16_bf16 v[2:17], v[50:53], v[58:61], v[2:17]
	s_waitcnt lgkmcnt(5)
	v_mfma_f32_32x32x16_bf16 v[18:33], v[70:73], v[62:65], v[18:33]
	s_waitcnt lgkmcnt(1)
	v_mfma_f32_32x32x16_bf16 v[2:17], v[66:69], v[86:89], v[2:17]
	v_mfma_f32_32x32x16_bf16 v[18:33], v[74:77], v[78:81], v[18:33]
	s_waitcnt lgkmcnt(0)
	v_mfma_f32_32x32x16_bf16 v[2:17], v[82:85], v[90:93], v[2:17]
	s_nop 9
	v_cvt_pk_bf16_f32 v18, v18, v19
	v_cvt_pk_bf16_f32 v19, v20, v21
	v_cvt_pk_bf16_f32 v20, v22, v23
	v_cvt_pk_bf16_f32 v23, v28, v29
	v_add_u32_e32 v28, 0x2000, v97
	v_cvt_pk_bf16_f32 v22, v26, v27
	v_or_b32_e32 v26, v28, v96
	v_cvt_pk_bf16_f32 v2, v2, v3
	v_cvt_pk_bf16_f32 v3, v4, v5
	v_cvt_pk_bf16_f32 v4, v6, v7
	v_or_b32_e32 v6, v28, v98
	v_ashrrev_i32_e32 v27, 31, v26
	v_ashrrev_i32_e32 v7, 31, v6
	v_cvt_pk_bf16_f32 v21, v24, v25
	v_lshl_add_u64 v[26:27], v[94:95], 0, v[26:27]
	v_cvt_pk_bf16_f32 v5, v8, v9
	v_lshl_add_u64 v[6:7], v[48:49], 0, v[6:7]
	v_cvt_pk_bf16_f32 v24, v30, v31
	v_cvt_pk_bf16_f32 v25, v32, v33
	global_store_dwordx4 v[26:27], v[18:21], off nt
	global_store_dwordx4 v[26:27], v[22:25], off offset:16 nt
	global_store_dwordx4 v[6:7], v[2:5], off nt
	s_nop 1
	v_cvt_pk_bf16_f32 v2, v10, v11
	v_cvt_pk_bf16_f32 v3, v12, v13
	v_cvt_pk_bf16_f32 v4, v14, v15
	v_cvt_pk_bf16_f32 v5, v16, v17
	global_store_dwordx4 v[6:7], v[2:5], off offset:1024 nt
	s_and_saveexec_b64 s[0:1], vcc
	s_cbranch_execz .LBB0_265
	v_mul_f32_e32 v0, 0x3fb8aa3b, v0
	v_exp_f32_e32 v0, v0
	v_readlane_b32 s22, v251, 60
	v_readlane_b32 s23, v251, 61
	s_nop 1
	v_lshl_add_u64 v[2:3], v[46:47], 2, s[22:23]
	global_store_dword v[2:3], v0, off
	s_branch .LBB0_265
.Ltramp_b45:
	s_branch .LBB0_9
.LBB0_336:
	s_mov_b64 s[0:1], 0

.LBB0_752:
	s_cmpk_lt_i32 s10, 0x3e8
	s_cbranch_scc0 .LBB0_806
	s_waitcnt vmcnt(0)
	s_waitcnt lgkmcnt(0)
	s_barrier
	s_cmp_eq_u32 s10, 4
	s_cbranch_scc1 .Ltramp_b45
	s_mov_b64 s[0:1], exec
	v_readlane_b32 s16, v250, 3
	v_readlane_b32 s17, v250, 4
	s_and_b64 s[16:17], s[0:1], s[16:17]
	s_mov_b64 exec, s[16:17]
	s_cbranch_execz .LBB0_805
	v_readlane_b32 s2, v254, 20
	s_waitcnt vmcnt(0) expcnt(0) lgkmcnt(0)
	s_nop 0
	v_mov_b32_e32 v0, s2
	ds_read_b32 v3, v0
	v_readlane_b32 s2, v254, 21
	s_waitcnt lgkmcnt(0)
	v_cmp_ne_u32_e32 vcc, 0, v3
	v_mov_b32_e32 v0, s2
	ds_read_b32 v2, v0
	s_cbranch_vccnz .LBB0_769
	s_mov_b32 s2, 1
	s_branch .LBB0_757
